# speedup vs baseline: 1.0186x; 1.0083x over previous
; template <int DH, int MODE>
; __device__ void attn_item(const Params& p, int layer, int b, int blk, int head, char* smem) {
;     ...
; #pragma unroll 2
;         for (int c = 7; c >= 0; --c) {
;           float4 v = s4[c];
;           float e[4] = {v.x, v.y, v.z, v.w};
; #pragma unroll
;           for (int k = 3; k >= 0; --k) {
;             float z = e[k];
;             bool valid = (kpb + c * 4 + k) < qpos;
;             float sp = fmaxf(z, 0.f) + __builtin_amdgcn_logf(1.f + __builtin_amdgcn_exp2f(-fabsf(z)));
;             run += valid ? -sp : 0.f;
;             e[k] = z + run;
;           }
;           s4[c] = make_float4(e[0], e[1], e[2], e[3]);
;         }
.LBB0_205:
	ds_read_b128 v[150:153], v148 offset:16
	ds_read_b128 v[176:179], v148
	v_add_u32_e32 v149, s52, v173
	v_add_u32_e32 v182, 0x3fdd, v149
	v_cmp_lt_i32_e32 vcc, v182, v144
	s_waitcnt lgkmcnt(1)
	v_exp_f32_e64 v175, -|v151|
	v_exp_f32_e64 v184, -|v150|
	v_max_f32_e32 v183, 0, v151
	v_add_f32_e32 v175, 1.0, v175
	v_log_f32_e32 v175, v175
	v_add_f32_e32 v182, 1.0, v184
	v_exp_f32_e64 v184, -|v153|
	v_add_u32_e32 v147, 0x3fdc, v149
	v_add_f32_e32 v175, v183, v175
	v_log_f32_e32 v182, v182
	v_cndmask_b32_e64 v175, 0, -v175, vcc
	v_cmp_lt_i32_e32 vcc, v147, v144
	v_add_f32_e32 v147, 1.0, v184
	v_exp_f32_e64 v184, -|v152|
	v_log_f32_e32 v147, v147
	v_max_f32_e32 v183, 0, v150
	v_add_u32_e32 v180, 0x3fdf, v149
	v_add_f32_e32 v182, v183, v182
	v_cndmask_b32_e64 v182, 0, -v182, vcc
	v_max_f32_e32 v183, 0, v153
	v_cmp_lt_i32_e32 vcc, v180, v144
	v_add_f32_e32 v180, 1.0, v184
	v_add_f32_e32 v147, v183, v147
	v_log_f32_e32 v180, v180
	v_cndmask_b32_e64 v147, 0, -v147, vcc
	v_add_f32_e32 v147, v146, v147
	v_add_u32_e32 v181, 0x3fde, v149
	v_max_f32_e32 v146, 0, v152
	v_add_f32_e32 v146, v146, v180
	v_cmp_lt_i32_e32 vcc, v181, v144
	s_add_i32 s52, s52, -8
	s_cmpk_eq_i32 s52, 0xffe0
	v_cndmask_b32_e64 v146, 0, -v146, vcc
	v_add_f32_e32 v146, v146, v147
	v_pk_add_f32 v[152:153], v[152:153], v[146:147]
	v_add_f32_e32 v147, v175, v146
	v_add_f32_e32 v146, v182, v147
	v_pk_add_f32 v[150:151], v[150:151], v[146:147]
	ds_write_b128 v148, v[150:153] offset:16
	s_waitcnt lgkmcnt(1)
	v_exp_f32_e64 v150, -|v177|
	v_exp_f32_e64 v175, -|v176|
	v_add_u32_e32 v147, 0x3fd8, v149
	v_add_f32_e32 v150, 1.0, v150
	v_log_f32_e32 v150, v150
	v_add_u32_e32 v151, 0x3fdb, v149
	v_add_u32_e32 v152, 0x3fda, v149
	v_add_u32_e32 v149, 0x3fd9, v149
	v_max_f32_e32 v153, 0, v177
	v_add_f32_e32 v150, v153, v150
	v_cmp_lt_i32_e32 vcc, v149, v144
	v_max_f32_e32 v153, 0, v176
	s_nop 0
	v_cndmask_b32_e64 v149, 0, -v150, vcc
	v_add_f32_e32 v150, 1.0, v175
	v_exp_f32_e64 v175, -|v179|
	v_log_f32_e32 v150, v150
	v_cmp_lt_i32_e32 vcc, v147, v144
	v_add_f32_e32 v147, 1.0, v175
	v_exp_f32_e64 v175, -|v178|
	v_log_f32_e32 v147, v147
	v_add_f32_e32 v150, v153, v150
	v_cndmask_b32_e64 v150, 0, -v150, vcc
	v_max_f32_e32 v153, 0, v179
	v_cmp_lt_i32_e32 vcc, v151, v144
	v_add_f32_e32 v151, 1.0, v175
	v_add_f32_e32 v147, v153, v147
	v_log_f32_e32 v151, v151
	v_cndmask_b32_e64 v147, 0, -v147, vcc
	v_add_f32_e32 v147, v146, v147
	v_max_f32_e32 v146, 0, v178
	v_add_f32_e32 v146, v146, v151
	v_cmp_lt_i32_e32 vcc, v152, v144
	s_nop 1
	v_cndmask_b32_e64 v146, 0, -v146, vcc
	v_add_f32_e32 v146, v146, v147
	v_pk_add_f32 v[152:153], v[178:179], v[146:147]
	v_add_f32_e32 v147, v149, v146
	v_add_f32_e32 v146, v150, v147
	v_pk_add_f32 v[150:151], v[176:177], v[146:147]
	ds_write_b128 v148, v[150:153]
	v_subrev_u32_e32 v148, 32, v148
	s_cbranch_scc0 .LBB0_205
; __device__ __forceinline__ unsigned pack2(float a, float b) { return (unsigned)f2bf(a) | ((unsigned)f2bf(b) << 16); }
; template <int DH, int MODE>
; __device__ void attn_item(const Params& p, int layer, int b, int blk, int head, char* smem) {
;     ...
;         float other = __shfl_xor(run, 1);
;         float offs = m_run + (half == 0 ? other : 0.f);
; #pragma unroll 2
;         for (int s8 = 0; s8 < 4; ++s8) {
;           float4 va = s4[2 * s8], vb = s4[2 * s8 + 1];
;           float e[8] = {va.x, va.y, va.z, va.w, vb.x, vb.y, vb.z, vb.w};
;           float pv[8];
; #pragma unroll
;           for (int k = 0; k < 8; ++k) {
;             bool valid = (kpb + s8 * 8 + k) < qpos;
;             pv[k] = valid ? __builtin_amdgcn_exp2f(e[k] + offs) : 0.f;
;           }
;           uint4 ov;
;           ov.x = pack2(pv[0], pv[1]); ov.y = pack2(pv[2], pv[3]);
;           ov.z = pack2(pv[4], pv[5]); ov.w = pack2(pv[6], pv[7]);
;           *reinterpret_cast<uint4*>(prow + s8 * 16) = ov;
;         }
	ds_bpermute_b32 v147, v163, v146
	s_mov_b32 s85, 0
	v_mov_b32_e32 v175, v168
	v_mov_b32_e32 v177, v167
	s_waitcnt lgkmcnt(0)
	v_cndmask_b32_e64 v148, 0, v147, s[6:7]
	v_add_f32_e32 v176, v174, v148
	ds_read_b128 v[180:183], v177
	ds_read_b128 v[184:187], v177 offset:16
	ds_read_b128 v[188:191], v177 offset:32
	ds_read_b128 v[192:195], v177 offset:48
	ds_read_b128 v[196:199], v177 offset:64
	ds_read_b128 v[200:203], v177 offset:80
	ds_read_b128 v[204:207], v177 offset:96
	ds_read_b128 v[208:211], v177 offset:112
	v_sub_u32_e32 v212, v144, v173
	v_add_u32_e32 v212, 0xffffc040, v212
	s_waitcnt lgkmcnt(7)
	v_add_f32_e32 v180, v176, v180
	v_add_f32_e32 v181, v176, v181
	v_add_f32_e32 v182, v176, v182
	v_exp_f32_e32 v180, v180
	v_exp_f32_e32 v181, v181
	v_exp_f32_e32 v182, v182
	v_cmp_lt_i32_e32 vcc, 0, v212
	v_cmp_lt_i32_e64 s[92:93], 1, v212
	v_cmp_lt_i32_e64 s[94:95], 2, v212
	v_cndmask_b32_e32 v180, 0, v180, vcc
	v_cndmask_b32_e64 v181, 0, v181, s[92:93]
	v_cndmask_b32_e64 v182, 0, v182, s[94:95]
	s_waitcnt lgkmcnt(6)
	v_add_f32_e32 v183, v176, v183
	v_add_f32_e32 v184, v176, v184
	v_add_f32_e32 v185, v176, v185
	v_exp_f32_e32 v183, v183
	v_exp_f32_e32 v184, v184
	v_exp_f32_e32 v185, v185
	v_cmp_lt_i32_e32 vcc, 3, v212
	v_cmp_lt_i32_e64 s[92:93], 4, v212
	v_cmp_lt_i32_e64 s[94:95], 5, v212
	v_cndmask_b32_e32 v183, 0, v183, vcc
	v_cndmask_b32_e64 v184, 0, v184, s[92:93]
	v_cndmask_b32_e64 v185, 0, v185, s[94:95]
	s_waitcnt lgkmcnt(5)
	v_add_f32_e32 v186, v176, v186
	v_add_f32_e32 v187, v176, v187
	v_add_f32_e32 v188, v176, v188
	v_exp_f32_e32 v186, v186
	v_exp_f32_e32 v187, v187
	v_exp_f32_e32 v188, v188
	v_cmp_lt_i32_e32 vcc, 6, v212
	v_cmp_lt_i32_e64 s[92:93], 7, v212
	v_cmp_lt_i32_e64 s[94:95], 8, v212
	v_cndmask_b32_e32 v186, 0, v186, vcc
	v_cndmask_b32_e64 v187, 0, v187, s[92:93]
	v_cndmask_b32_e64 v188, 0, v188, s[94:95]
	v_add_f32_e32 v189, v176, v189
	v_add_f32_e32 v190, v176, v190
	v_add_f32_e32 v191, v176, v191
	v_exp_f32_e32 v189, v189
	v_exp_f32_e32 v190, v190
	v_exp_f32_e32 v191, v191
	v_cmp_lt_i32_e32 vcc, 9, v212
	v_cmp_lt_i32_e64 s[92:93], 10, v212
	v_cmp_lt_i32_e64 s[94:95], 11, v212
	v_cndmask_b32_e32 v189, 0, v189, vcc
	v_cndmask_b32_e64 v190, 0, v190, s[92:93]
	v_cndmask_b32_e64 v191, 0, v191, s[94:95]
	s_waitcnt lgkmcnt(4)
	v_add_f32_e32 v192, v176, v192
	v_add_f32_e32 v193, v176, v193
	v_add_f32_e32 v194, v176, v194
	v_exp_f32_e32 v192, v192
	v_exp_f32_e32 v193, v193
	v_exp_f32_e32 v194, v194
	v_cmp_lt_i32_e32 vcc, 12, v212
	v_cmp_lt_i32_e64 s[92:93], 13, v212
	v_cmp_lt_i32_e64 s[94:95], 14, v212
	v_cndmask_b32_e32 v192, 0, v192, vcc
	v_cndmask_b32_e64 v193, 0, v193, s[92:93]
	v_cndmask_b32_e64 v194, 0, v194, s[94:95]
	s_waitcnt lgkmcnt(3)
	v_add_f32_e32 v195, v176, v195
	v_add_f32_e32 v196, v176, v196
	v_add_f32_e32 v197, v176, v197
	v_exp_f32_e32 v195, v195
	v_exp_f32_e32 v196, v196
	v_exp_f32_e32 v197, v197
	v_cmp_lt_i32_e32 vcc, 15, v212
	v_cmp_lt_i32_e64 s[92:93], 16, v212
	v_cmp_lt_i32_e64 s[94:95], 17, v212
	v_cndmask_b32_e32 v195, 0, v195, vcc
	v_cndmask_b32_e64 v196, 0, v196, s[92:93]
	v_cndmask_b32_e64 v197, 0, v197, s[94:95]
	s_waitcnt lgkmcnt(2)
	v_add_f32_e32 v198, v176, v198
	v_add_f32_e32 v199, v176, v199
	v_add_f32_e32 v200, v176, v200
	v_exp_f32_e32 v198, v198
	v_exp_f32_e32 v199, v199
	v_exp_f32_e32 v200, v200
	v_cmp_lt_i32_e32 vcc, 18, v212
	v_cmp_lt_i32_e64 s[92:93], 19, v212
	v_cmp_lt_i32_e64 s[94:95], 20, v212
	v_cndmask_b32_e32 v198, 0, v198, vcc
	v_cndmask_b32_e64 v199, 0, v199, s[92:93]
	v_cndmask_b32_e64 v200, 0, v200, s[94:95]
	v_add_f32_e32 v201, v176, v201
	v_add_f32_e32 v202, v176, v202
	v_add_f32_e32 v203, v176, v203
	v_exp_f32_e32 v201, v201
	v_exp_f32_e32 v202, v202
	v_exp_f32_e32 v203, v203
	v_cmp_lt_i32_e32 vcc, 21, v212
	v_cmp_lt_i32_e64 s[92:93], 22, v212
	v_cmp_lt_i32_e64 s[94:95], 23, v212
	v_cndmask_b32_e32 v201, 0, v201, vcc
	v_cndmask_b32_e64 v202, 0, v202, s[92:93]
	v_cndmask_b32_e64 v203, 0, v203, s[94:95]
	s_waitcnt lgkmcnt(1)
	v_add_f32_e32 v204, v176, v204
	v_add_f32_e32 v205, v176, v205
	v_add_f32_e32 v206, v176, v206
	v_exp_f32_e32 v204, v204
	v_exp_f32_e32 v205, v205
	v_exp_f32_e32 v206, v206
	v_cmp_lt_i32_e32 vcc, 24, v212
	v_cmp_lt_i32_e64 s[92:93], 25, v212
	v_cmp_lt_i32_e64 s[94:95], 26, v212
	v_cndmask_b32_e32 v204, 0, v204, vcc
	v_cndmask_b32_e64 v205, 0, v205, s[92:93]
	v_cndmask_b32_e64 v206, 0, v206, s[94:95]
	s_waitcnt lgkmcnt(0)
	v_add_f32_e32 v207, v176, v207
	v_add_f32_e32 v208, v176, v208
	v_add_f32_e32 v209, v176, v209
	v_exp_f32_e32 v207, v207
	v_exp_f32_e32 v208, v208
	v_exp_f32_e32 v209, v209
	v_cmp_lt_i32_e32 vcc, 27, v212
	v_cmp_lt_i32_e64 s[92:93], 28, v212
	v_cmp_lt_i32_e64 s[94:95], 29, v212
	v_cndmask_b32_e32 v207, 0, v207, vcc
	v_cndmask_b32_e64 v208, 0, v208, s[92:93]
	v_cndmask_b32_e64 v209, 0, v209, s[94:95]
	v_add_f32_e32 v210, v176, v210
	v_add_f32_e32 v211, v176, v211
	v_exp_f32_e32 v210, v210
	v_exp_f32_e32 v211, v211
	v_cmp_lt_i32_e32 vcc, 30, v212
	v_cmp_lt_i32_e64 s[92:93], 31, v212
	s_nop 0
	v_cndmask_b32_e32 v210, 0, v210, vcc
	v_cndmask_b32_e64 v211, 0, v211, s[92:93]
	v_cvt_pk_bf16_f32 v148, v180, v181
	v_cvt_pk_bf16_f32 v149, v182, v183
	v_cvt_pk_bf16_f32 v150, v184, v185
	v_cvt_pk_bf16_f32 v151, v186, v187
	ds_write_b128 v175, v[148:151]
	s_nop 0
	v_cvt_pk_bf16_f32 v148, v188, v189
	v_cvt_pk_bf16_f32 v149, v190, v191
	v_cvt_pk_bf16_f32 v150, v192, v193
	v_cvt_pk_bf16_f32 v151, v194, v195
	ds_write_b128 v175, v[148:151] offset:16
	s_nop 0
	v_cvt_pk_bf16_f32 v148, v196, v197
	v_cvt_pk_bf16_f32 v149, v198, v199
	v_cvt_pk_bf16_f32 v150, v200, v201
	v_cvt_pk_bf16_f32 v151, v202, v203
	ds_write_b128 v175, v[148:151] offset:32
	s_nop 0
	v_cvt_pk_bf16_f32 v148, v204, v205
	v_cvt_pk_bf16_f32 v149, v206, v207
	v_cvt_pk_bf16_f32 v150, v208, v209
	v_cvt_pk_bf16_f32 v151, v210, v211
	ds_write_b128 v175, v[148:151] offset:48
	s_branch .LBB0_213

; template <int DH, int MODE>
; __device__ void attn_item(const Params& p, int layer, int b, int blk, int head, char* smem) {
;     ...
; #pragma unroll 2
;         for (int c = 7; c >= 0; --c) {
;           float4 v = s4[c];
;           float e[4] = {v.x, v.y, v.z, v.w};
; #pragma unroll
;           for (int k = 3; k >= 0; --k) {
;             float z = e[k];
;             bool valid = (kpb + c * 4 + k) < qpos;
;             float sp = fmaxf(z, 0.f) + __builtin_amdgcn_logf(1.f + __builtin_amdgcn_exp2f(-fabsf(z)));
;             run += valid ? -sp : 0.f;
;             e[k] = z + run;
;           }
;           s4[c] = make_float4(e[0], e[1], e[2], e[3]);
;         }
.LBB0_526:
	ds_read_b128 v[150:153], v148 offset:16
	ds_read_b128 v[176:179], v148
	v_add_u32_e32 v149, s54, v173
	v_add_u32_e32 v182, 0x3fdd, v149
	v_cmp_lt_i32_e32 vcc, v182, v144
	s_waitcnt lgkmcnt(1)
	v_exp_f32_e64 v175, -|v151|
	v_exp_f32_e64 v184, -|v150|
	v_max_f32_e32 v183, 0, v151
	v_add_f32_e32 v175, 1.0, v175
	v_log_f32_e32 v175, v175
	v_add_f32_e32 v182, 1.0, v184
	v_exp_f32_e64 v184, -|v153|
	v_add_u32_e32 v147, 0x3fdc, v149
	v_add_f32_e32 v175, v183, v175
	v_log_f32_e32 v182, v182
	v_cndmask_b32_e64 v175, 0, -v175, vcc
	v_cmp_lt_i32_e32 vcc, v147, v144
	v_add_f32_e32 v147, 1.0, v184
	v_exp_f32_e64 v184, -|v152|
	v_log_f32_e32 v147, v147
	v_max_f32_e32 v183, 0, v150
	v_add_u32_e32 v180, 0x3fdf, v149
	v_add_f32_e32 v182, v183, v182
	v_cndmask_b32_e64 v182, 0, -v182, vcc
	v_max_f32_e32 v183, 0, v153
	v_cmp_lt_i32_e32 vcc, v180, v144
	v_add_f32_e32 v180, 1.0, v184
	v_add_f32_e32 v147, v183, v147
	v_log_f32_e32 v180, v180
	v_cndmask_b32_e64 v147, 0, -v147, vcc
	v_add_f32_e32 v147, v146, v147
	v_add_u32_e32 v181, 0x3fde, v149
	v_max_f32_e32 v146, 0, v152
	v_add_f32_e32 v146, v146, v180
	v_cmp_lt_i32_e32 vcc, v181, v144
	s_add_i32 s54, s54, -8
	s_cmpk_eq_i32 s54, 0xffe0
	v_cndmask_b32_e64 v146, 0, -v146, vcc
	v_add_f32_e32 v146, v146, v147
	v_pk_add_f32 v[152:153], v[152:153], v[146:147]
	v_add_f32_e32 v147, v175, v146
	v_add_f32_e32 v146, v182, v147
	v_pk_add_f32 v[150:151], v[150:151], v[146:147]
	ds_write_b128 v148, v[150:153] offset:16
	s_waitcnt lgkmcnt(1)
	v_exp_f32_e64 v150, -|v177|
	v_exp_f32_e64 v175, -|v176|
	v_add_u32_e32 v147, 0x3fd8, v149
	v_add_f32_e32 v150, 1.0, v150
	v_log_f32_e32 v150, v150
	v_add_u32_e32 v151, 0x3fdb, v149
	v_add_u32_e32 v152, 0x3fda, v149
	v_add_u32_e32 v149, 0x3fd9, v149
	v_max_f32_e32 v153, 0, v177
	v_add_f32_e32 v150, v153, v150
	v_cmp_lt_i32_e32 vcc, v149, v144
	v_max_f32_e32 v153, 0, v176
	s_nop 0
	v_cndmask_b32_e64 v149, 0, -v150, vcc
	v_add_f32_e32 v150, 1.0, v175
	v_exp_f32_e64 v175, -|v179|
	v_log_f32_e32 v150, v150
	v_cmp_lt_i32_e32 vcc, v147, v144
	v_add_f32_e32 v147, 1.0, v175
	v_exp_f32_e64 v175, -|v178|
	v_log_f32_e32 v147, v147
	v_add_f32_e32 v150, v153, v150
	v_cndmask_b32_e64 v150, 0, -v150, vcc
	v_max_f32_e32 v153, 0, v179
	v_cmp_lt_i32_e32 vcc, v151, v144
	v_add_f32_e32 v151, 1.0, v175
	v_add_f32_e32 v147, v153, v147
	v_log_f32_e32 v151, v151
	v_cndmask_b32_e64 v147, 0, -v147, vcc
	v_add_f32_e32 v147, v146, v147
	v_max_f32_e32 v146, 0, v178
	v_add_f32_e32 v146, v146, v151
	v_cmp_lt_i32_e32 vcc, v152, v144
	s_nop 1
	v_cndmask_b32_e64 v146, 0, -v146, vcc
	v_add_f32_e32 v146, v146, v147
	v_pk_add_f32 v[152:153], v[178:179], v[146:147]
	v_add_f32_e32 v147, v149, v146
	v_add_f32_e32 v146, v150, v147
	v_pk_add_f32 v[150:151], v[176:177], v[146:147]
	ds_write_b128 v148, v[150:153]
	v_subrev_u32_e32 v148, 32, v148
	s_cbranch_scc0 .LBB0_526
; __device__ __forceinline__ unsigned pack2(float a, float b) { return (unsigned)f2bf(a) | ((unsigned)f2bf(b) << 16); }
; template <int DH, int MODE>
; __device__ void attn_item(const Params& p, int layer, int b, int blk, int head, char* smem) {
;     ...
;         float other = __shfl_xor(run, 1);
;         float offs = m_run + (half == 0 ? other : 0.f);
; #pragma unroll 2
;         for (int s8 = 0; s8 < 4; ++s8) {
;           float4 va = s4[2 * s8], vb = s4[2 * s8 + 1];
;           float e[8] = {va.x, va.y, va.z, va.w, vb.x, vb.y, vb.z, vb.w};
;           float pv[8];
; #pragma unroll
;           for (int k = 0; k < 8; ++k) {
;             bool valid = (kpb + s8 * 8 + k) < qpos;
;             pv[k] = valid ? __builtin_amdgcn_exp2f(e[k] + offs) : 0.f;
;           }
;           uint4 ov;
;           ov.x = pack2(pv[0], pv[1]); ov.y = pack2(pv[2], pv[3]);
;           ov.z = pack2(pv[4], pv[5]); ov.w = pack2(pv[6], pv[7]);
;           *reinterpret_cast<uint4*>(prow + s8 * 16) = ov;
;         }
	ds_bpermute_b32 v147, v163, v146
	s_mov_b32 s88, 0
	v_mov_b32_e32 v175, v168
	v_mov_b32_e32 v177, v167
	s_waitcnt lgkmcnt(0)
	v_cndmask_b32_e64 v148, 0, v147, s[14:15]
	v_add_f32_e32 v176, v174, v148
	ds_read_b128 v[180:183], v177
	ds_read_b128 v[184:187], v177 offset:16
	ds_read_b128 v[188:191], v177 offset:32
	ds_read_b128 v[192:195], v177 offset:48
	ds_read_b128 v[196:199], v177 offset:64
	ds_read_b128 v[200:203], v177 offset:80
	ds_read_b128 v[204:207], v177 offset:96
	ds_read_b128 v[208:211], v177 offset:112
	v_sub_u32_e32 v212, v144, v173
	v_add_u32_e32 v212, 0xffffc040, v212
	s_waitcnt lgkmcnt(7)
	v_add_f32_e32 v180, v176, v180
	v_add_f32_e32 v181, v176, v181
	v_add_f32_e32 v182, v176, v182
	v_exp_f32_e32 v180, v180
	v_exp_f32_e32 v181, v181
	v_exp_f32_e32 v182, v182
	v_cmp_lt_i32_e32 vcc, 0, v212
	v_cmp_lt_i32_e64 s[92:93], 1, v212
	v_cmp_lt_i32_e64 s[94:95], 2, v212
	v_cndmask_b32_e32 v180, 0, v180, vcc
	v_cndmask_b32_e64 v181, 0, v181, s[92:93]
	v_cndmask_b32_e64 v182, 0, v182, s[94:95]
	s_waitcnt lgkmcnt(6)
	v_add_f32_e32 v183, v176, v183
	v_add_f32_e32 v184, v176, v184
	v_add_f32_e32 v185, v176, v185
	v_exp_f32_e32 v183, v183
	v_exp_f32_e32 v184, v184
	v_exp_f32_e32 v185, v185
	v_cmp_lt_i32_e32 vcc, 3, v212
	v_cmp_lt_i32_e64 s[92:93], 4, v212
	v_cmp_lt_i32_e64 s[94:95], 5, v212
	v_cndmask_b32_e32 v183, 0, v183, vcc
	v_cndmask_b32_e64 v184, 0, v184, s[92:93]
	v_cndmask_b32_e64 v185, 0, v185, s[94:95]
	s_waitcnt lgkmcnt(5)
	v_add_f32_e32 v186, v176, v186
	v_add_f32_e32 v187, v176, v187
	v_add_f32_e32 v188, v176, v188
	v_exp_f32_e32 v186, v186
	v_exp_f32_e32 v187, v187
	v_exp_f32_e32 v188, v188
	v_cmp_lt_i32_e32 vcc, 6, v212
	v_cmp_lt_i32_e64 s[92:93], 7, v212
	v_cmp_lt_i32_e64 s[94:95], 8, v212
	v_cndmask_b32_e32 v186, 0, v186, vcc
	v_cndmask_b32_e64 v187, 0, v187, s[92:93]
	v_cndmask_b32_e64 v188, 0, v188, s[94:95]
	v_add_f32_e32 v189, v176, v189
	v_add_f32_e32 v190, v176, v190
	v_add_f32_e32 v191, v176, v191
	v_exp_f32_e32 v189, v189
	v_exp_f32_e32 v190, v190
	v_exp_f32_e32 v191, v191
	v_cmp_lt_i32_e32 vcc, 9, v212
	v_cmp_lt_i32_e64 s[92:93], 10, v212
	v_cmp_lt_i32_e64 s[94:95], 11, v212
	v_cndmask_b32_e32 v189, 0, v189, vcc
	v_cndmask_b32_e64 v190, 0, v190, s[92:93]
	v_cndmask_b32_e64 v191, 0, v191, s[94:95]
	s_waitcnt lgkmcnt(4)
	v_add_f32_e32 v192, v176, v192
	v_add_f32_e32 v193, v176, v193
	v_add_f32_e32 v194, v176, v194
	v_exp_f32_e32 v192, v192
	v_exp_f32_e32 v193, v193
	v_exp_f32_e32 v194, v194
	v_cmp_lt_i32_e32 vcc, 12, v212
	v_cmp_lt_i32_e64 s[92:93], 13, v212
	v_cmp_lt_i32_e64 s[94:95], 14, v212
	v_cndmask_b32_e32 v192, 0, v192, vcc
	v_cndmask_b32_e64 v193, 0, v193, s[92:93]
	v_cndmask_b32_e64 v194, 0, v194, s[94:95]
	s_waitcnt lgkmcnt(3)
	v_add_f32_e32 v195, v176, v195
	v_add_f32_e32 v196, v176, v196
	v_add_f32_e32 v197, v176, v197
	v_exp_f32_e32 v195, v195
	v_exp_f32_e32 v196, v196
	v_exp_f32_e32 v197, v197
	v_cmp_lt_i32_e32 vcc, 15, v212
	v_cmp_lt_i32_e64 s[92:93], 16, v212
	v_cmp_lt_i32_e64 s[94:95], 17, v212
	v_cndmask_b32_e32 v195, 0, v195, vcc
	v_cndmask_b32_e64 v196, 0, v196, s[92:93]
	v_cndmask_b32_e64 v197, 0, v197, s[94:95]
	s_waitcnt lgkmcnt(2)
	v_add_f32_e32 v198, v176, v198
	v_add_f32_e32 v199, v176, v199
	v_add_f32_e32 v200, v176, v200
	v_exp_f32_e32 v198, v198
	v_exp_f32_e32 v199, v199
	v_exp_f32_e32 v200, v200
	v_cmp_lt_i32_e32 vcc, 18, v212
	v_cmp_lt_i32_e64 s[92:93], 19, v212
	v_cmp_lt_i32_e64 s[94:95], 20, v212
	v_cndmask_b32_e32 v198, 0, v198, vcc
	v_cndmask_b32_e64 v199, 0, v199, s[92:93]
	v_cndmask_b32_e64 v200, 0, v200, s[94:95]
	v_add_f32_e32 v201, v176, v201
	v_add_f32_e32 v202, v176, v202
	v_add_f32_e32 v203, v176, v203
	v_exp_f32_e32 v201, v201
	v_exp_f32_e32 v202, v202
	v_exp_f32_e32 v203, v203
	v_cmp_lt_i32_e32 vcc, 21, v212
	v_cmp_lt_i32_e64 s[92:93], 22, v212
	v_cmp_lt_i32_e64 s[94:95], 23, v212
	v_cndmask_b32_e32 v201, 0, v201, vcc
	v_cndmask_b32_e64 v202, 0, v202, s[92:93]
	v_cndmask_b32_e64 v203, 0, v203, s[94:95]
	s_waitcnt lgkmcnt(1)
	v_add_f32_e32 v204, v176, v204
	v_add_f32_e32 v205, v176, v205
	v_add_f32_e32 v206, v176, v206
	v_exp_f32_e32 v204, v204
	v_exp_f32_e32 v205, v205
	v_exp_f32_e32 v206, v206
	v_cmp_lt_i32_e32 vcc, 24, v212
	v_cmp_lt_i32_e64 s[92:93], 25, v212
	v_cmp_lt_i32_e64 s[94:95], 26, v212
	v_cndmask_b32_e32 v204, 0, v204, vcc
	v_cndmask_b32_e64 v205, 0, v205, s[92:93]
	v_cndmask_b32_e64 v206, 0, v206, s[94:95]
	s_waitcnt lgkmcnt(0)
	v_add_f32_e32 v207, v176, v207
	v_add_f32_e32 v208, v176, v208
	v_add_f32_e32 v209, v176, v209
	v_exp_f32_e32 v207, v207
	v_exp_f32_e32 v208, v208
	v_exp_f32_e32 v209, v209
	v_cmp_lt_i32_e32 vcc, 27, v212
	v_cmp_lt_i32_e64 s[92:93], 28, v212
	v_cmp_lt_i32_e64 s[94:95], 29, v212
	v_cndmask_b32_e32 v207, 0, v207, vcc
	v_cndmask_b32_e64 v208, 0, v208, s[92:93]
	v_cndmask_b32_e64 v209, 0, v209, s[94:95]
	v_add_f32_e32 v210, v176, v210
	v_add_f32_e32 v211, v176, v211
	v_exp_f32_e32 v210, v210
	v_exp_f32_e32 v211, v211
	v_cmp_lt_i32_e32 vcc, 30, v212
	v_cmp_lt_i32_e64 s[92:93], 31, v212
	s_nop 0
	v_cndmask_b32_e32 v210, 0, v210, vcc
	v_cndmask_b32_e64 v211, 0, v211, s[92:93]
	v_cvt_pk_bf16_f32 v148, v180, v181
	v_cvt_pk_bf16_f32 v149, v182, v183
	v_cvt_pk_bf16_f32 v150, v184, v185
	v_cvt_pk_bf16_f32 v151, v186, v187
	ds_write_b128 v175, v[148:151]
	s_nop 0
	v_cvt_pk_bf16_f32 v148, v188, v189
	v_cvt_pk_bf16_f32 v149, v190, v191
	v_cvt_pk_bf16_f32 v150, v192, v193
	v_cvt_pk_bf16_f32 v151, v194, v195
	ds_write_b128 v175, v[148:151] offset:16
	s_nop 0
	v_cvt_pk_bf16_f32 v148, v196, v197
	v_cvt_pk_bf16_f32 v149, v198, v199
	v_cvt_pk_bf16_f32 v150, v200, v201
	v_cvt_pk_bf16_f32 v151, v202, v203
	ds_write_b128 v175, v[148:151] offset:32
	s_nop 0
	v_cvt_pk_bf16_f32 v148, v204, v205
	v_cvt_pk_bf16_f32 v149, v206, v207
	v_cvt_pk_bf16_f32 v150, v208, v209
	v_cvt_pk_bf16_f32 v151, v210, v211
	ds_write_b128 v175, v[148:151] offset:48
	s_branch .LBB0_534

; template <int DH, int MODE>
; __device__ void attn_item(const Params& p, int layer, int b, int blk, int head, char* smem) {
;     ...
; #pragma unroll 2
;         for (int c = 7; c >= 0; --c) {
;           float4 v = s4[c];
;           float e[4] = {v.x, v.y, v.z, v.w};
; #pragma unroll
;           for (int k = 3; k >= 0; --k) {
;             float z = e[k];
;             bool valid = (kpb + c * 4 + k) < qpos;
;             float sp = fmaxf(z, 0.f) + __builtin_amdgcn_logf(1.f + __builtin_amdgcn_exp2f(-fabsf(z)));
;             run += valid ? -sp : 0.f;
;             e[k] = z + run;
;           }
;           s4[c] = make_float4(e[0], e[1], e[2], e[3]);
;         }
.LBB0_847:
	ds_read_b128 v[150:153], v148 offset:16
	ds_read_b128 v[176:179], v148
	v_add_u32_e32 v149, s52, v173
	v_add_u32_e32 v182, 0x3fdd, v149
	v_cmp_lt_i32_e32 vcc, v182, v144
	s_waitcnt lgkmcnt(1)
	v_exp_f32_e64 v175, -|v151|
	v_exp_f32_e64 v184, -|v150|
	v_max_f32_e32 v183, 0, v151
	v_add_f32_e32 v175, 1.0, v175
	v_log_f32_e32 v175, v175
	v_add_f32_e32 v182, 1.0, v184
	v_exp_f32_e64 v184, -|v153|
	v_add_u32_e32 v147, 0x3fdc, v149
	v_add_f32_e32 v175, v183, v175
	v_log_f32_e32 v182, v182
	v_cndmask_b32_e64 v175, 0, -v175, vcc
	v_cmp_lt_i32_e32 vcc, v147, v144
	v_add_f32_e32 v147, 1.0, v184
	v_exp_f32_e64 v184, -|v152|
	v_log_f32_e32 v147, v147
	v_max_f32_e32 v183, 0, v150
	v_add_u32_e32 v180, 0x3fdf, v149
	v_add_f32_e32 v182, v183, v182
	v_cndmask_b32_e64 v182, 0, -v182, vcc
	v_max_f32_e32 v183, 0, v153
	v_cmp_lt_i32_e32 vcc, v180, v144
	v_add_f32_e32 v180, 1.0, v184
	v_add_f32_e32 v147, v183, v147
	v_log_f32_e32 v180, v180
	v_cndmask_b32_e64 v147, 0, -v147, vcc
	v_add_f32_e32 v147, v146, v147
	v_add_u32_e32 v181, 0x3fde, v149
	v_max_f32_e32 v146, 0, v152
	v_add_f32_e32 v146, v146, v180
	v_cmp_lt_i32_e32 vcc, v181, v144
	s_add_i32 s52, s52, -8
	s_cmpk_eq_i32 s52, 0xffe0
	v_cndmask_b32_e64 v146, 0, -v146, vcc
	v_add_f32_e32 v146, v146, v147
	v_pk_add_f32 v[152:153], v[152:153], v[146:147]
	v_add_f32_e32 v147, v175, v146
	v_add_f32_e32 v146, v182, v147
	v_pk_add_f32 v[150:151], v[150:151], v[146:147]
	ds_write_b128 v148, v[150:153] offset:16
	s_waitcnt lgkmcnt(1)
	v_exp_f32_e64 v150, -|v177|
	v_exp_f32_e64 v175, -|v176|
	v_add_u32_e32 v147, 0x3fd8, v149
	v_add_f32_e32 v150, 1.0, v150
	v_log_f32_e32 v150, v150
	v_add_u32_e32 v151, 0x3fdb, v149
	v_add_u32_e32 v152, 0x3fda, v149
	v_add_u32_e32 v149, 0x3fd9, v149
	v_max_f32_e32 v153, 0, v177
	v_add_f32_e32 v150, v153, v150
	v_cmp_lt_i32_e32 vcc, v149, v144
	v_max_f32_e32 v153, 0, v176
	s_nop 0
	v_cndmask_b32_e64 v149, 0, -v150, vcc
	v_add_f32_e32 v150, 1.0, v175
	v_exp_f32_e64 v175, -|v179|
	v_log_f32_e32 v150, v150
	v_cmp_lt_i32_e32 vcc, v147, v144
	v_add_f32_e32 v147, 1.0, v175
	v_exp_f32_e64 v175, -|v178|
	v_log_f32_e32 v147, v147
	v_add_f32_e32 v150, v153, v150
	v_cndmask_b32_e64 v150, 0, -v150, vcc
	v_max_f32_e32 v153, 0, v179
	v_cmp_lt_i32_e32 vcc, v151, v144
	v_add_f32_e32 v151, 1.0, v175
	v_add_f32_e32 v147, v153, v147
	v_log_f32_e32 v151, v151
	v_cndmask_b32_e64 v147, 0, -v147, vcc
	v_add_f32_e32 v147, v146, v147
	v_max_f32_e32 v146, 0, v178
	v_add_f32_e32 v146, v146, v151
	v_cmp_lt_i32_e32 vcc, v152, v144
	s_nop 1
	v_cndmask_b32_e64 v146, 0, -v146, vcc
	v_add_f32_e32 v146, v146, v147
	v_pk_add_f32 v[152:153], v[178:179], v[146:147]
	v_add_f32_e32 v147, v149, v146
	v_add_f32_e32 v146, v150, v147
	v_pk_add_f32 v[150:151], v[176:177], v[146:147]
	ds_write_b128 v148, v[150:153]
	v_subrev_u32_e32 v148, 32, v148
	s_cbranch_scc0 .LBB0_847
; __device__ __forceinline__ unsigned pack2(float a, float b) { return (unsigned)f2bf(a) | ((unsigned)f2bf(b) << 16); }
; template <int DH, int MODE>
; __device__ void attn_item(const Params& p, int layer, int b, int blk, int head, char* smem) {
;     ...
;         float other = __shfl_xor(run, 1);
;         float offs = m_run + (half == 0 ? other : 0.f);
; #pragma unroll 2
;         for (int s8 = 0; s8 < 4; ++s8) {
;           float4 va = s4[2 * s8], vb = s4[2 * s8 + 1];
;           float e[8] = {va.x, va.y, va.z, va.w, vb.x, vb.y, vb.z, vb.w};
;           float pv[8];
; #pragma unroll
;           for (int k = 0; k < 8; ++k) {
;             bool valid = (kpb + s8 * 8 + k) < qpos;
;             pv[k] = valid ? __builtin_amdgcn_exp2f(e[k] + offs) : 0.f;
;           }
;           uint4 ov;
;           ov.x = pack2(pv[0], pv[1]); ov.y = pack2(pv[2], pv[3]);
;           ov.z = pack2(pv[4], pv[5]); ov.w = pack2(pv[6], pv[7]);
;           *reinterpret_cast<uint4*>(prow + s8 * 16) = ov;
;         }
	ds_bpermute_b32 v147, v163, v146
	s_mov_b32 s88, 0
	v_mov_b32_e32 v175, v168
	v_mov_b32_e32 v177, v167
	s_waitcnt lgkmcnt(0)
	v_cndmask_b32_e64 v148, 0, v147, s[14:15]
	v_add_f32_e32 v176, v174, v148
	ds_read_b128 v[180:183], v177
	ds_read_b128 v[184:187], v177 offset:16
	ds_read_b128 v[188:191], v177 offset:32
	ds_read_b128 v[192:195], v177 offset:48
	ds_read_b128 v[196:199], v177 offset:64
	ds_read_b128 v[200:203], v177 offset:80
	ds_read_b128 v[204:207], v177 offset:96
	ds_read_b128 v[208:211], v177 offset:112
	v_sub_u32_e32 v212, v144, v173
	v_add_u32_e32 v212, 0xffffc040, v212
	s_waitcnt lgkmcnt(7)
	v_add_f32_e32 v180, v176, v180
	v_add_f32_e32 v181, v176, v181
	v_add_f32_e32 v182, v176, v182
	v_exp_f32_e32 v180, v180
	v_exp_f32_e32 v181, v181
	v_exp_f32_e32 v182, v182
	v_cmp_lt_i32_e32 vcc, 0, v212
	v_cmp_lt_i32_e64 s[92:93], 1, v212
	v_cmp_lt_i32_e64 s[94:95], 2, v212
	v_cndmask_b32_e32 v180, 0, v180, vcc
	v_cndmask_b32_e64 v181, 0, v181, s[92:93]
	v_cndmask_b32_e64 v182, 0, v182, s[94:95]
	s_waitcnt lgkmcnt(6)
	v_add_f32_e32 v183, v176, v183
	v_add_f32_e32 v184, v176, v184
	v_add_f32_e32 v185, v176, v185
	v_exp_f32_e32 v183, v183
	v_exp_f32_e32 v184, v184
	v_exp_f32_e32 v185, v185
	v_cmp_lt_i32_e32 vcc, 3, v212
	v_cmp_lt_i32_e64 s[92:93], 4, v212
	v_cmp_lt_i32_e64 s[94:95], 5, v212
	v_cndmask_b32_e32 v183, 0, v183, vcc
	v_cndmask_b32_e64 v184, 0, v184, s[92:93]
	v_cndmask_b32_e64 v185, 0, v185, s[94:95]
	s_waitcnt lgkmcnt(5)
	v_add_f32_e32 v186, v176, v186
	v_add_f32_e32 v187, v176, v187
	v_add_f32_e32 v188, v176, v188
	v_exp_f32_e32 v186, v186
	v_exp_f32_e32 v187, v187
	v_exp_f32_e32 v188, v188
	v_cmp_lt_i32_e32 vcc, 6, v212
	v_cmp_lt_i32_e64 s[92:93], 7, v212
	v_cmp_lt_i32_e64 s[94:95], 8, v212
	v_cndmask_b32_e32 v186, 0, v186, vcc
	v_cndmask_b32_e64 v187, 0, v187, s[92:93]
	v_cndmask_b32_e64 v188, 0, v188, s[94:95]
	v_add_f32_e32 v189, v176, v189
	v_add_f32_e32 v190, v176, v190
	v_add_f32_e32 v191, v176, v191
	v_exp_f32_e32 v189, v189
	v_exp_f32_e32 v190, v190
	v_exp_f32_e32 v191, v191
	v_cmp_lt_i32_e32 vcc, 9, v212
	v_cmp_lt_i32_e64 s[92:93], 10, v212
	v_cmp_lt_i32_e64 s[94:95], 11, v212
	v_cndmask_b32_e32 v189, 0, v189, vcc
	v_cndmask_b32_e64 v190, 0, v190, s[92:93]
	v_cndmask_b32_e64 v191, 0, v191, s[94:95]
	s_waitcnt lgkmcnt(4)
	v_add_f32_e32 v192, v176, v192
	v_add_f32_e32 v193, v176, v193
	v_add_f32_e32 v194, v176, v194
	v_exp_f32_e32 v192, v192
	v_exp_f32_e32 v193, v193
	v_exp_f32_e32 v194, v194
	v_cmp_lt_i32_e32 vcc, 12, v212
	v_cmp_lt_i32_e64 s[92:93], 13, v212
	v_cmp_lt_i32_e64 s[94:95], 14, v212
	v_cndmask_b32_e32 v192, 0, v192, vcc
	v_cndmask_b32_e64 v193, 0, v193, s[92:93]
	v_cndmask_b32_e64 v194, 0, v194, s[94:95]
	s_waitcnt lgkmcnt(3)
	v_add_f32_e32 v195, v176, v195
	v_add_f32_e32 v196, v176, v196
	v_add_f32_e32 v197, v176, v197
	v_exp_f32_e32 v195, v195
	v_exp_f32_e32 v196, v196
	v_exp_f32_e32 v197, v197
	v_cmp_lt_i32_e32 vcc, 15, v212
	v_cmp_lt_i32_e64 s[92:93], 16, v212
	v_cmp_lt_i32_e64 s[94:95], 17, v212
	v_cndmask_b32_e32 v195, 0, v195, vcc
	v_cndmask_b32_e64 v196, 0, v196, s[92:93]
	v_cndmask_b32_e64 v197, 0, v197, s[94:95]
	s_waitcnt lgkmcnt(2)
	v_add_f32_e32 v198, v176, v198
	v_add_f32_e32 v199, v176, v199
	v_add_f32_e32 v200, v176, v200
	v_exp_f32_e32 v198, v198
	v_exp_f32_e32 v199, v199
	v_exp_f32_e32 v200, v200
	v_cmp_lt_i32_e32 vcc, 18, v212
	v_cmp_lt_i32_e64 s[92:93], 19, v212
	v_cmp_lt_i32_e64 s[94:95], 20, v212
	v_cndmask_b32_e32 v198, 0, v198, vcc
	v_cndmask_b32_e64 v199, 0, v199, s[92:93]
	v_cndmask_b32_e64 v200, 0, v200, s[94:95]
	v_add_f32_e32 v201, v176, v201
	v_add_f32_e32 v202, v176, v202
	v_add_f32_e32 v203, v176, v203
	v_exp_f32_e32 v201, v201
	v_exp_f32_e32 v202, v202
	v_exp_f32_e32 v203, v203
	v_cmp_lt_i32_e32 vcc, 21, v212
	v_cmp_lt_i32_e64 s[92:93], 22, v212
	v_cmp_lt_i32_e64 s[94:95], 23, v212
	v_cndmask_b32_e32 v201, 0, v201, vcc
	v_cndmask_b32_e64 v202, 0, v202, s[92:93]
	v_cndmask_b32_e64 v203, 0, v203, s[94:95]
	s_waitcnt lgkmcnt(1)
	v_add_f32_e32 v204, v176, v204
	v_add_f32_e32 v205, v176, v205
	v_add_f32_e32 v206, v176, v206
	v_exp_f32_e32 v204, v204
	v_exp_f32_e32 v205, v205
	v_exp_f32_e32 v206, v206
	v_cmp_lt_i32_e32 vcc, 24, v212
	v_cmp_lt_i32_e64 s[92:93], 25, v212
	v_cmp_lt_i32_e64 s[94:95], 26, v212
	v_cndmask_b32_e32 v204, 0, v204, vcc
	v_cndmask_b32_e64 v205, 0, v205, s[92:93]
	v_cndmask_b32_e64 v206, 0, v206, s[94:95]
	s_waitcnt lgkmcnt(0)
	v_add_f32_e32 v207, v176, v207
	v_add_f32_e32 v208, v176, v208
	v_add_f32_e32 v209, v176, v209
	v_exp_f32_e32 v207, v207
	v_exp_f32_e32 v208, v208
	v_exp_f32_e32 v209, v209
	v_cmp_lt_i32_e32 vcc, 27, v212
	v_cmp_lt_i32_e64 s[92:93], 28, v212
	v_cmp_lt_i32_e64 s[94:95], 29, v212
	v_cndmask_b32_e32 v207, 0, v207, vcc
	v_cndmask_b32_e64 v208, 0, v208, s[92:93]
	v_cndmask_b32_e64 v209, 0, v209, s[94:95]
	v_add_f32_e32 v210, v176, v210
	v_add_f32_e32 v211, v176, v211
	v_exp_f32_e32 v210, v210
	v_exp_f32_e32 v211, v211
	v_cmp_lt_i32_e32 vcc, 30, v212
	v_cmp_lt_i32_e64 s[92:93], 31, v212
	s_nop 0
	v_cndmask_b32_e32 v210, 0, v210, vcc
	v_cndmask_b32_e64 v211, 0, v211, s[92:93]
	v_cvt_pk_bf16_f32 v148, v180, v181
	v_cvt_pk_bf16_f32 v149, v182, v183
	v_cvt_pk_bf16_f32 v150, v184, v185
	v_cvt_pk_bf16_f32 v151, v186, v187
	ds_write_b128 v175, v[148:151]
	s_nop 0
	v_cvt_pk_bf16_f32 v148, v188, v189
	v_cvt_pk_bf16_f32 v149, v190, v191
	v_cvt_pk_bf16_f32 v150, v192, v193
	v_cvt_pk_bf16_f32 v151, v194, v195
	ds_write_b128 v175, v[148:151] offset:16
	s_nop 0
	v_cvt_pk_bf16_f32 v148, v196, v197
	v_cvt_pk_bf16_f32 v149, v198, v199
	v_cvt_pk_bf16_f32 v150, v200, v201
	v_cvt_pk_bf16_f32 v151, v202, v203
	ds_write_b128 v175, v[148:151] offset:32
	s_nop 0
	v_cvt_pk_bf16_f32 v148, v204, v205
	v_cvt_pk_bf16_f32 v149, v206, v207
	v_cvt_pk_bf16_f32 v150, v208, v209
	v_cvt_pk_bf16_f32 v151, v210, v211
	ds_write_b128 v175, v[148:151] offset:48
	s_branch .LBB0_855

; template <int DH, int MODE>
; __device__ void attn_item(const Params& p, int layer, int b, int blk, int head, char* smem) {
;     ...
; #pragma unroll 2
;         for (int c = 7; c >= 0; --c) {
;           float4 v = s4[c];
;           float e[4] = {v.x, v.y, v.z, v.w};
; #pragma unroll
;           for (int k = 3; k >= 0; --k) {
;             float z = e[k];
;             bool valid = (kpb + c * 4 + k) < qpos;
;             float sp = fmaxf(z, 0.f) + __builtin_amdgcn_logf(1.f + __builtin_amdgcn_exp2f(-fabsf(z)));
;             run += valid ? -sp : 0.f;
;             e[k] = z + run;
;           }
;           s4[c] = make_float4(e[0], e[1], e[2], e[3]);
;         }
.LBB0_1168:
	ds_read_b128 v[150:153], v148 offset:16
	ds_read_b128 v[176:179], v148
	v_add_u32_e32 v149, s46, v173
	v_add_u32_e32 v182, 0x3fdd, v149
	v_cmp_lt_i32_e32 vcc, v182, v144
	s_waitcnt lgkmcnt(1)
	v_exp_f32_e64 v175, -|v151|
	v_exp_f32_e64 v184, -|v150|
	v_max_f32_e32 v183, 0, v151
	v_add_f32_e32 v175, 1.0, v175
	v_log_f32_e32 v175, v175
	v_add_f32_e32 v182, 1.0, v184
	v_exp_f32_e64 v184, -|v153|
	v_add_u32_e32 v147, 0x3fdc, v149
	v_add_f32_e32 v175, v183, v175
	v_log_f32_e32 v182, v182
	v_cndmask_b32_e64 v175, 0, -v175, vcc
	v_cmp_lt_i32_e32 vcc, v147, v144
	v_add_f32_e32 v147, 1.0, v184
	v_exp_f32_e64 v184, -|v152|
	v_log_f32_e32 v147, v147
	v_max_f32_e32 v183, 0, v150
	v_add_u32_e32 v180, 0x3fdf, v149
	v_add_f32_e32 v182, v183, v182
	v_cndmask_b32_e64 v182, 0, -v182, vcc
	v_max_f32_e32 v183, 0, v153
	v_cmp_lt_i32_e32 vcc, v180, v144
	v_add_f32_e32 v180, 1.0, v184
	v_add_f32_e32 v147, v183, v147
	v_log_f32_e32 v180, v180
	v_cndmask_b32_e64 v147, 0, -v147, vcc
	v_add_f32_e32 v147, v146, v147
	v_add_u32_e32 v181, 0x3fde, v149
	v_max_f32_e32 v146, 0, v152
	v_add_f32_e32 v146, v146, v180
	v_cmp_lt_i32_e32 vcc, v181, v144
	s_add_i32 s46, s46, -8
	s_cmpk_eq_i32 s46, 0xffe0
	v_cndmask_b32_e64 v146, 0, -v146, vcc
	v_add_f32_e32 v146, v146, v147
	v_pk_add_f32 v[152:153], v[152:153], v[146:147]
	v_add_f32_e32 v147, v175, v146
	v_add_f32_e32 v146, v182, v147
	v_pk_add_f32 v[150:151], v[150:151], v[146:147]
	ds_write_b128 v148, v[150:153] offset:16
	s_waitcnt lgkmcnt(1)
	v_exp_f32_e64 v150, -|v177|
	v_exp_f32_e64 v175, -|v176|
	v_add_u32_e32 v147, 0x3fd8, v149
	v_add_f32_e32 v150, 1.0, v150
	v_log_f32_e32 v150, v150
	v_add_u32_e32 v151, 0x3fdb, v149
	v_add_u32_e32 v152, 0x3fda, v149
	v_add_u32_e32 v149, 0x3fd9, v149
	v_max_f32_e32 v153, 0, v177
	v_add_f32_e32 v150, v153, v150
	v_cmp_lt_i32_e32 vcc, v149, v144
	v_max_f32_e32 v153, 0, v176
	s_nop 0
	v_cndmask_b32_e64 v149, 0, -v150, vcc
	v_add_f32_e32 v150, 1.0, v175
	v_exp_f32_e64 v175, -|v179|
	v_log_f32_e32 v150, v150
	v_cmp_lt_i32_e32 vcc, v147, v144
	v_add_f32_e32 v147, 1.0, v175
	v_exp_f32_e64 v175, -|v178|
	v_log_f32_e32 v147, v147
	v_add_f32_e32 v150, v153, v150
	v_cndmask_b32_e64 v150, 0, -v150, vcc
	v_max_f32_e32 v153, 0, v179
	v_cmp_lt_i32_e32 vcc, v151, v144
	v_add_f32_e32 v151, 1.0, v175
	v_add_f32_e32 v147, v153, v147
	v_log_f32_e32 v151, v151
	v_cndmask_b32_e64 v147, 0, -v147, vcc
	v_add_f32_e32 v147, v146, v147
	v_max_f32_e32 v146, 0, v178
	v_add_f32_e32 v146, v146, v151
	v_cmp_lt_i32_e32 vcc, v152, v144
	s_nop 1
	v_cndmask_b32_e64 v146, 0, -v146, vcc
	v_add_f32_e32 v146, v146, v147
	v_pk_add_f32 v[152:153], v[178:179], v[146:147]
	v_add_f32_e32 v147, v149, v146
	v_add_f32_e32 v146, v150, v147
	v_pk_add_f32 v[150:151], v[176:177], v[146:147]
	ds_write_b128 v148, v[150:153]
	v_subrev_u32_e32 v148, 32, v148
	s_cbranch_scc0 .LBB0_1168
; __device__ __forceinline__ unsigned pack2(float a, float b) { return (unsigned)f2bf(a) | ((unsigned)f2bf(b) << 16); }
; template <int DH, int MODE>
; __device__ void attn_item(const Params& p, int layer, int b, int blk, int head, char* smem) {
;     ...
;         float other = __shfl_xor(run, 1);
;         float offs = m_run + (half == 0 ? other : 0.f);
; #pragma unroll 2
;         for (int s8 = 0; s8 < 4; ++s8) {
;           float4 va = s4[2 * s8], vb = s4[2 * s8 + 1];
;           float e[8] = {va.x, va.y, va.z, va.w, vb.x, vb.y, vb.z, vb.w};
;           float pv[8];
; #pragma unroll
;           for (int k = 0; k < 8; ++k) {
;             bool valid = (kpb + s8 * 8 + k) < qpos;
;             pv[k] = valid ? __builtin_amdgcn_exp2f(e[k] + offs) : 0.f;
;           }
;           uint4 ov;
;           ov.x = pack2(pv[0], pv[1]); ov.y = pack2(pv[2], pv[3]);
;           ov.z = pack2(pv[4], pv[5]); ov.w = pack2(pv[6], pv[7]);
;           *reinterpret_cast<uint4*>(prow + s8 * 16) = ov;
;         }
	ds_bpermute_b32 v147, v163, v146
	s_mov_b32 s81, 0
	v_mov_b32_e32 v175, v168
	v_mov_b32_e32 v177, v167
	s_waitcnt lgkmcnt(0)
	v_cndmask_b32_e64 v148, 0, v147, s[8:9]
	v_add_f32_e32 v176, v174, v148
	ds_read_b128 v[180:183], v177
	ds_read_b128 v[184:187], v177 offset:16
	ds_read_b128 v[188:191], v177 offset:32
	ds_read_b128 v[192:195], v177 offset:48
	ds_read_b128 v[196:199], v177 offset:64
	ds_read_b128 v[200:203], v177 offset:80
	ds_read_b128 v[204:207], v177 offset:96
	ds_read_b128 v[208:211], v177 offset:112
	v_sub_u32_e32 v212, v144, v173
	v_add_u32_e32 v212, 0xffffc040, v212
	s_waitcnt lgkmcnt(7)
	v_add_f32_e32 v180, v176, v180
	v_add_f32_e32 v181, v176, v181
	v_add_f32_e32 v182, v176, v182
	v_exp_f32_e32 v180, v180
	v_exp_f32_e32 v181, v181
	v_exp_f32_e32 v182, v182
	v_cmp_lt_i32_e32 vcc, 0, v212
	v_cmp_lt_i32_e64 s[92:93], 1, v212
	v_cmp_lt_i32_e64 s[94:95], 2, v212
	v_cndmask_b32_e32 v180, 0, v180, vcc
	v_cndmask_b32_e64 v181, 0, v181, s[92:93]
	v_cndmask_b32_e64 v182, 0, v182, s[94:95]
	s_waitcnt lgkmcnt(6)
	v_add_f32_e32 v183, v176, v183
	v_add_f32_e32 v184, v176, v184
	v_add_f32_e32 v185, v176, v185
	v_exp_f32_e32 v183, v183
	v_exp_f32_e32 v184, v184
	v_exp_f32_e32 v185, v185
	v_cmp_lt_i32_e32 vcc, 3, v212
	v_cmp_lt_i32_e64 s[92:93], 4, v212
	v_cmp_lt_i32_e64 s[94:95], 5, v212
	v_cndmask_b32_e32 v183, 0, v183, vcc
	v_cndmask_b32_e64 v184, 0, v184, s[92:93]
	v_cndmask_b32_e64 v185, 0, v185, s[94:95]
	s_waitcnt lgkmcnt(5)
	v_add_f32_e32 v186, v176, v186
	v_add_f32_e32 v187, v176, v187
	v_add_f32_e32 v188, v176, v188
	v_exp_f32_e32 v186, v186
	v_exp_f32_e32 v187, v187
	v_exp_f32_e32 v188, v188
	v_cmp_lt_i32_e32 vcc, 6, v212
	v_cmp_lt_i32_e64 s[92:93], 7, v212
	v_cmp_lt_i32_e64 s[94:95], 8, v212
	v_cndmask_b32_e32 v186, 0, v186, vcc
	v_cndmask_b32_e64 v187, 0, v187, s[92:93]
	v_cndmask_b32_e64 v188, 0, v188, s[94:95]
	v_add_f32_e32 v189, v176, v189
	v_add_f32_e32 v190, v176, v190
	v_add_f32_e32 v191, v176, v191
	v_exp_f32_e32 v189, v189
	v_exp_f32_e32 v190, v190
	v_exp_f32_e32 v191, v191
	v_cmp_lt_i32_e32 vcc, 9, v212
	v_cmp_lt_i32_e64 s[92:93], 10, v212
	v_cmp_lt_i32_e64 s[94:95], 11, v212
	v_cndmask_b32_e32 v189, 0, v189, vcc
	v_cndmask_b32_e64 v190, 0, v190, s[92:93]
	v_cndmask_b32_e64 v191, 0, v191, s[94:95]
	s_waitcnt lgkmcnt(4)
	v_add_f32_e32 v192, v176, v192
	v_add_f32_e32 v193, v176, v193
	v_add_f32_e32 v194, v176, v194
	v_exp_f32_e32 v192, v192
	v_exp_f32_e32 v193, v193
	v_exp_f32_e32 v194, v194
	v_cmp_lt_i32_e32 vcc, 12, v212
	v_cmp_lt_i32_e64 s[92:93], 13, v212
	v_cmp_lt_i32_e64 s[94:95], 14, v212
	v_cndmask_b32_e32 v192, 0, v192, vcc
	v_cndmask_b32_e64 v193, 0, v193, s[92:93]
	v_cndmask_b32_e64 v194, 0, v194, s[94:95]
	s_waitcnt lgkmcnt(3)
	v_add_f32_e32 v195, v176, v195
	v_add_f32_e32 v196, v176, v196
	v_add_f32_e32 v197, v176, v197
	v_exp_f32_e32 v195, v195
	v_exp_f32_e32 v196, v196
	v_exp_f32_e32 v197, v197
	v_cmp_lt_i32_e32 vcc, 15, v212
	v_cmp_lt_i32_e64 s[92:93], 16, v212
	v_cmp_lt_i32_e64 s[94:95], 17, v212
	v_cndmask_b32_e32 v195, 0, v195, vcc
	v_cndmask_b32_e64 v196, 0, v196, s[92:93]
	v_cndmask_b32_e64 v197, 0, v197, s[94:95]
	s_waitcnt lgkmcnt(2)
	v_add_f32_e32 v198, v176, v198
	v_add_f32_e32 v199, v176, v199
	v_add_f32_e32 v200, v176, v200
	v_exp_f32_e32 v198, v198
	v_exp_f32_e32 v199, v199
	v_exp_f32_e32 v200, v200
	v_cmp_lt_i32_e32 vcc, 18, v212
	v_cmp_lt_i32_e64 s[92:93], 19, v212
	v_cmp_lt_i32_e64 s[94:95], 20, v212
	v_cndmask_b32_e32 v198, 0, v198, vcc
	v_cndmask_b32_e64 v199, 0, v199, s[92:93]
	v_cndmask_b32_e64 v200, 0, v200, s[94:95]
	v_add_f32_e32 v201, v176, v201
	v_add_f32_e32 v202, v176, v202
	v_add_f32_e32 v203, v176, v203
	v_exp_f32_e32 v201, v201
	v_exp_f32_e32 v202, v202
	v_exp_f32_e32 v203, v203
	v_cmp_lt_i32_e32 vcc, 21, v212
	v_cmp_lt_i32_e64 s[92:93], 22, v212
	v_cmp_lt_i32_e64 s[94:95], 23, v212
	v_cndmask_b32_e32 v201, 0, v201, vcc
	v_cndmask_b32_e64 v202, 0, v202, s[92:93]
	v_cndmask_b32_e64 v203, 0, v203, s[94:95]
	s_waitcnt lgkmcnt(1)
	v_add_f32_e32 v204, v176, v204
	v_add_f32_e32 v205, v176, v205
	v_add_f32_e32 v206, v176, v206
	v_exp_f32_e32 v204, v204
	v_exp_f32_e32 v205, v205
	v_exp_f32_e32 v206, v206
	v_cmp_lt_i32_e32 vcc, 24, v212
	v_cmp_lt_i32_e64 s[92:93], 25, v212
	v_cmp_lt_i32_e64 s[94:95], 26, v212
	v_cndmask_b32_e32 v204, 0, v204, vcc
	v_cndmask_b32_e64 v205, 0, v205, s[92:93]
	v_cndmask_b32_e64 v206, 0, v206, s[94:95]
	s_waitcnt lgkmcnt(0)
	v_add_f32_e32 v207, v176, v207
	v_add_f32_e32 v208, v176, v208
	v_add_f32_e32 v209, v176, v209
	v_exp_f32_e32 v207, v207
	v_exp_f32_e32 v208, v208
	v_exp_f32_e32 v209, v209
	v_cmp_lt_i32_e32 vcc, 27, v212
	v_cmp_lt_i32_e64 s[92:93], 28, v212
	v_cmp_lt_i32_e64 s[94:95], 29, v212
	v_cndmask_b32_e32 v207, 0, v207, vcc
	v_cndmask_b32_e64 v208, 0, v208, s[92:93]
	v_cndmask_b32_e64 v209, 0, v209, s[94:95]
	v_add_f32_e32 v210, v176, v210
	v_add_f32_e32 v211, v176, v211
	v_exp_f32_e32 v210, v210
	v_exp_f32_e32 v211, v211
	v_cmp_lt_i32_e32 vcc, 30, v212
	v_cmp_lt_i32_e64 s[92:93], 31, v212
	s_nop 0
	v_cndmask_b32_e32 v210, 0, v210, vcc
	v_cndmask_b32_e64 v211, 0, v211, s[92:93]
	v_cvt_pk_bf16_f32 v148, v180, v181
	v_cvt_pk_bf16_f32 v149, v182, v183
	v_cvt_pk_bf16_f32 v150, v184, v185
	v_cvt_pk_bf16_f32 v151, v186, v187
	ds_write_b128 v175, v[148:151]
	s_nop 0
	v_cvt_pk_bf16_f32 v148, v188, v189
	v_cvt_pk_bf16_f32 v149, v190, v191
	v_cvt_pk_bf16_f32 v150, v192, v193
	v_cvt_pk_bf16_f32 v151, v194, v195
	ds_write_b128 v175, v[148:151] offset:16
	s_nop 0
	v_cvt_pk_bf16_f32 v148, v196, v197
	v_cvt_pk_bf16_f32 v149, v198, v199
	v_cvt_pk_bf16_f32 v150, v200, v201
	v_cvt_pk_bf16_f32 v151, v202, v203
	ds_write_b128 v175, v[148:151] offset:32
	s_nop 0
	v_cvt_pk_bf16_f32 v148, v204, v205
	v_cvt_pk_bf16_f32 v149, v206, v207
	v_cvt_pk_bf16_f32 v150, v208, v209
	v_cvt_pk_bf16_f32 v151, v210, v211
	ds_write_b128 v175, v[148:151] offset:48
	s_branch .LBB0_1176
